# v18_prio
# speedup vs baseline: 1.0367x; 1.0048x over previous
; #define STAGE(PP, RSRC, br, kt) do { const int _so = ((br) * K + (kt) * BK) * 2; \
;       __builtin_amdgcn_raw_ptr_buffer_load_lds(RSRC, LDSP((char*)(PP) + ldsoff), 16, voff0, _so, 0, 0); \
;       __builtin_amdgcn_raw_ptr_buffer_load_lds(RSRC, LDSP((char*)(PP) + ldsoff + 8192), 16, voff1, _so, 0, 0); \
;     } while (0)
; #define LDA(dst, b, h) for (int m = 0; m < 4; ++m) for (int k = 0; k < 2; ++k) \
;     dst[m][k] = *reinterpret_cast<const bf16x8*>((char*)SA(b, h) + lds_byte(wr * 64 + m * 16 + fr, k * 32 + fq * 8))
; #define LDB(dst, b, h) for (int n = 0; n < 2; ++n) for (int k = 0; k < 2; ++k) \
;     dst[n][k] = *reinterpret_cast<const bf16x8*>((char*)SB(b, h) + lds_byte(wc * 32 + n * 16 + fr, k * 32 + fq * 8))
; #define MMA(ai, bj, At_, Bt_) do { __builtin_amdgcn_s_setprio(1); \
;     for (int m = 0; m < 4; ++m) for (int n = 0; n < 2; ++n) for (int k = 0; k < 2; ++k) \
;       acc[ai][bj][m][n] = __builtin_amdgcn_mfma_f32_16x16x32_bf16(At_[m][k], Bt_[n][k], acc[ai][bj][m][n], 0, 0, 0); \
;     __builtin_amdgcn_s_setprio(0); } while (0)
; #define WAIT_V(n) asm volatile("s_waitcnt vmcnt(" #n ")" ::: "memory")
; #define WAIT_L(n) asm volatile("s_waitcnt lgkmcnt(" #n ")" ::: "memory")
; #define BAR __builtin_amdgcn_s_barrier()
; #define SCHED __builtin_amdgcn_sched_barrier(0)
; __device__ __forceinline__ void gemm_tile(const Params& P, const GArgs& ga, const TileDesc& td, int wid_s) {
;     ...
;   for (int t = 0; t < nt - 2; t += 2) {
;     LDA(At, 0, 0); STAGE(SA(1, 1), A, brow + HALF, t + 1);
;     WAIT_L(8); BAR; WAIT_L(0); MMA(0, 0, At, B0); BAR; SCHED;
;     LDB(B1, 0, 1); STAGE(SB(0, 0), Bt, bcol, t + 2);
;     BAR; WAIT_L(0); MMA(0, 1, At, B1); BAR;
;     LDA(At, 0, 1); STAGE(SA(0, 0), A, brow, t + 2);
;     WAIT_V(4); BAR; WAIT_L(0); MMA(1, 0, At, B0); BAR; SCHED;
;     LDB(B0, 1, 0); STAGE(SB(0, 1), Bt, bcol + HALF, t + 2);
;     BAR; MMA(1, 1, At, B1); BAR;
;     LDA(At, 1, 0); STAGE(SA(0, 1), A, brow + HALF, t + 2);
;     WAIT_L(8); BAR; WAIT_L(0); MMA(0, 0, At, B0); BAR; SCHED;
.LBB0_306:
	s_andn2_b64 vcc, exec, s[0:1]
	v_mov_b32_e32 v141, 0
	s_cbranch_vccnz .LBB0_310
	v_and_b32_e32 v22, 0x3c0, v22
	v_and_b32_e32 v23, 32, v23
	v_bitop3_b32 v150, v22, v23, v18 bitop3:0x36
	v_lshlrev_b32_e32 v23, 6, v21
	v_lshlrev_b32_e32 v21, 2, v21
	v_and_b32_e32 v23, 0x3c0, v23
	v_and_b32_e32 v21, 32, v21
	v_bitop3_b32 v152, v23, v21, v18 bitop3:0x36
	v_lshlrev_b32_e32 v23, 6, v20
	v_lshlrev_b32_e32 v20, 2, v20
	v_and_b32_e32 v23, 0x3c0, v23
	v_and_b32_e32 v20, 32, v20
	s_add_i32 s1, 0, 0x14000
	v_bitop3_b32 v154, v23, v20, v18 bitop3:0x36
	v_lshlrev_b32_e32 v23, 6, v19
	v_lshlrev_b32_e32 v19, 2, v19
	v_add_u32_e32 v24, s1, v146
	s_add_i32 s1, 0, 0x18000
	v_and_b32_e32 v23, 0x3c0, v23
	v_and_b32_e32 v19, 32, v19
	v_add_u32_e32 v25, s1, v146
	s_add_i32 s1, 0, 0x1c000
	v_bitop3_b32 v156, v23, v19, v18 bitop3:0x36
	v_add_u32_e32 v26, s1, v146
	v_add_u32_e32 v22, 0, v150
	v_add_u32_e32 v21, 0, v152
	v_add_u32_e32 v20, 0, v154
	v_add_u32_e32 v19, 0, v156
	s_add_i32 s1, s84, 0x80
	s_add_i32 s6, s92, 0x80
	v_mov_b32_e32 v18, 0
	s_add_i32 s0, s17, -2
	v_or_b32_e32 v151, 0x400, v159
	v_or_b32_e32 v153, 0x400, v161
	v_or_b32_e32 v155, 0x400, v160
	v_or_b32_e32 v157, 0x400, v158
	s_mul_i32 s1, s48, s1
	s_mul_i32 s98, s48, s6
	s_mov_b32 s99, 0
	v_add_u32_e32 v163, v22, v159
	v_add_u32_e32 v164, v21, v161
	v_add_u32_e32 v165, v20, v160
	v_add_u32_e32 v166, v19, v158
	v_add_u32_e32 v167, v24, v147
	v_add_u32_e32 v168, v25, v147
	v_add_u32_e32 v169, v26, v147
	s_mov_b32 vcc_lo, 0
	s_waitcnt vmcnt(15)
	s_waitcnt vmcnt(14)
	s_add_i32 s38, s1, s99
	s_add_i32 s6, s38, 0x80
	s_mov_b32 m0, s23
	ds_read_b128 v[170:173], v163
	ds_read_b128 v[174:177], v163 offset:1024
	ds_read_b128 v[178:181], v164
	ds_read_b128 v[182:185], v164 offset:1024
	ds_read_b128 v[186:189], v165
	ds_read_b128 v[190:193], v165 offset:1024
	ds_read_b128 v[194:197], v166
	ds_read_b128 v[204:207], v166 offset:1024
	buffer_load_dwordx4 v148, s[8:11], s6 offen lds
	s_mov_b32 m0, s22
	s_nop 0
	buffer_load_dwordx4 v149, s[8:11], s6 offen lds
	s_mul_i32 s6, s49, s15
	s_add_i32 s58, s6, s99
	s_mov_b32 m0, s88
	s_add_i32 vcc_hi, s58, 0x100
	s_mov_b32 s6, s10
	s_mov_b32 s7, s11
	ds_read_b128 v[208:211], v167
	ds_read_b128 v[212:215], v167 offset:1024
	ds_read_b128 v[216:219], v167 offset:2048
	ds_read_b128 v[220:223], v167 offset:3072
	buffer_load_dwordx4 v148, s[4:7], vcc_hi offen lds
	s_mov_b32 m0, s89
	s_add_i32 vcc_lo, vcc_lo, 2
	buffer_load_dwordx4 v149, s[4:7], vcc_hi offen lds
	s_waitcnt vmcnt(8) lgkmcnt(0)
	s_setprio 1
	s_barrier
	v_mfma_f32_16x16x32_bf16 v[138:141], v[170:173], v[2:5], 0
	v_mfma_f32_16x16x32_bf16 v[142:145], v[170:173], v[10:13], 0
	v_mfma_f32_16x16x32_bf16 v[134:137], v[178:181], v[2:5], 0
	v_mfma_f32_16x16x32_bf16 v[130:133], v[178:181], v[10:13], 0
	v_mfma_f32_16x16x32_bf16 v[126:129], v[186:189], v[2:5], 0
	v_mfma_f32_16x16x32_bf16 v[122:125], v[186:189], v[10:13], 0
	v_mfma_f32_16x16x32_bf16 v[118:121], v[194:197], v[2:5], 0
	v_mfma_f32_16x16x32_bf16 v[114:117], v[194:197], v[10:13], 0
	v_mfma_f32_16x16x32_bf16 v[138:141], v[174:177], v[6:9], v[138:141]
	v_mfma_f32_16x16x32_bf16 v[142:145], v[174:177], v[14:17], v[142:145]
	v_mfma_f32_16x16x32_bf16 v[134:137], v[182:185], v[6:9], v[134:137]
	v_mfma_f32_16x16x32_bf16 v[130:133], v[182:185], v[14:17], v[130:133]
	v_mfma_f32_16x16x32_bf16 v[126:129], v[190:193], v[6:9], v[126:129]
	v_mfma_f32_16x16x32_bf16 v[122:125], v[190:193], v[14:17], v[122:125]
	v_mfma_f32_16x16x32_bf16 v[118:121], v[204:207], v[6:9], v[118:121]
	v_mfma_f32_16x16x32_bf16 v[114:117], v[204:207], v[14:17], v[114:117]
	v_mfma_f32_16x16x32_bf16 v[110:113], v[170:173], v[208:211], 0
	v_mfma_f32_16x16x32_bf16 v[106:109], v[170:173], v[216:219], 0
	v_mfma_f32_16x16x32_bf16 v[102:105], v[178:181], v[208:211], 0
	v_mfma_f32_16x16x32_bf16 v[98:101], v[178:181], v[216:219], 0
	v_mfma_f32_16x16x32_bf16 v[94:97], v[186:189], v[208:211], 0
	v_mfma_f32_16x16x32_bf16 v[90:93], v[186:189], v[216:219], 0
	v_mfma_f32_16x16x32_bf16 v[86:89], v[194:197], v[208:211], 0
	v_mfma_f32_16x16x32_bf16 v[82:85], v[194:197], v[216:219], 0
	v_mfma_f32_16x16x32_bf16 v[110:113], v[174:177], v[212:215], v[110:113]
	v_mfma_f32_16x16x32_bf16 v[106:109], v[174:177], v[220:223], v[106:109]
	v_mfma_f32_16x16x32_bf16 v[102:105], v[182:185], v[212:215], v[102:105]
	v_mfma_f32_16x16x32_bf16 v[98:101], v[182:185], v[220:223], v[98:101]
	v_mfma_f32_16x16x32_bf16 v[94:97], v[190:193], v[212:215], v[94:97]
	v_mfma_f32_16x16x32_bf16 v[90:93], v[190:193], v[220:223], v[90:93]
	v_mfma_f32_16x16x32_bf16 v[86:89], v[204:207], v[212:215], v[86:89]
	v_mfma_f32_16x16x32_bf16 v[82:85], v[204:207], v[220:223], v[82:85]
	s_barrier
	s_setprio 0
	s_mul_i32 vcc_hi, s49, s86
	s_add_i32 s40, vcc_hi, s99
	s_add_i32 vcc_hi, s40, 0x100
	s_mov_b32 m0, s52
	ds_read_b128 v[170:173], v163 offset:16384
	ds_read_b128 v[174:177], v163 offset:17408
	ds_read_b128 v[178:181], v164 offset:16384
	ds_read_b128 v[182:185], v164 offset:17408
	ds_read_b128 v[186:189], v165 offset:16384
	ds_read_b128 v[190:193], v165 offset:17408
	ds_read_b128 v[194:197], v166 offset:16384
	ds_read_b128 v[204:207], v166 offset:17408
	buffer_load_dwordx4 v148, s[8:11], vcc_hi offen lds
	s_mov_b32 m0, s94
	s_nop 0
	buffer_load_dwordx4 v149, s[8:11], vcc_hi offen lds
	s_add_i32 s33, s98, s99
	s_add_i32 vcc_hi, s33, 0x100
	s_mov_b32 m0, s95
	ds_read_b128 v[232:235], v168
	ds_read_b128 v[236:239], v168 offset:1024
	ds_read_b128 v[240:243], v168 offset:2048
	ds_read_b128 v[244:247], v168 offset:3072
	buffer_load_dwordx4 v148, s[4:7], vcc_hi offen lds
	s_mov_b32 m0, s3
	s_nop 0
	buffer_load_dwordx4 v149, s[4:7], vcc_hi offen lds
	s_waitcnt vmcnt(8) lgkmcnt(0)
	s_setprio 1
	s_barrier
; #define STAGE(PP, RSRC, br, kt) do { const int _so = ((br) * K + (kt) * BK) * 2; \
;       __builtin_amdgcn_raw_ptr_buffer_load_lds(RSRC, LDSP((char*)(PP) + ldsoff), 16, voff0, _so, 0, 0); \
;       __builtin_amdgcn_raw_ptr_buffer_load_lds(RSRC, LDSP((char*)(PP) + ldsoff + 8192), 16, voff1, _so, 0, 0); \
;     } while (0)
; #define LDA(dst, b, h) for (int m = 0; m < 4; ++m) for (int k = 0; k < 2; ++k) \
;     dst[m][k] = *reinterpret_cast<const bf16x8*>((char*)SA(b, h) + lds_byte(wr * 64 + m * 16 + fr, k * 32 + fq * 8))
; #define LDB(dst, b, h) for (int n = 0; n < 2; ++n) for (int k = 0; k < 2; ++k) \
;     dst[n][k] = *reinterpret_cast<const bf16x8*>((char*)SB(b, h) + lds_byte(wc * 32 + n * 16 + fr, k * 32 + fq * 8))
; #define MMA(ai, bj, At_, Bt_) do { __builtin_amdgcn_s_setprio(1); \
;     for (int m = 0; m < 4; ++m) for (int n = 0; n < 2; ++n) for (int k = 0; k < 2; ++k) \
;       acc[ai][bj][m][n] = __builtin_amdgcn_mfma_f32_16x16x32_bf16(At_[m][k], Bt_[n][k], acc[ai][bj][m][n], 0, 0, 0); \
;     __builtin_amdgcn_s_setprio(0); } while (0)
; #define WAIT_V(n) asm volatile("s_waitcnt vmcnt(" #n ")" ::: "memory")
; #define WAIT_L(n) asm volatile("s_waitcnt lgkmcnt(" #n ")" ::: "memory")
; #define BAR __builtin_amdgcn_s_barrier()
; #define SCHED __builtin_amdgcn_sched_barrier(0)
; __device__ __forceinline__ void gemm_tile(const Params& P, const GArgs& ga, const TileDesc& td, int wid_s) {
;     ...
;     BAR; WAIT_L(0); MMA(0, 1, At, B1); BAR;
;     LDA(At, 0, 1); STAGE(SA(0, 0), A, brow, t + 2);
;     WAIT_V(4); BAR; WAIT_L(0); MMA(1, 0, At, B0); BAR; SCHED;
;     LDB(B0, 1, 0); STAGE(SB(0, 1), Bt, bcol + HALF, t + 2);
;     BAR; MMA(1, 1, At, B1); BAR;
;     LDA(At, 1, 0); STAGE(SA(0, 1), A, brow + HALF, t + 2);
;     WAIT_L(8); BAR; WAIT_L(0); MMA(0, 0, At, B0); BAR; SCHED;
	v_mfma_f32_16x16x32_bf16 v[78:81], v[170:173], v[2:5], 0
	v_mfma_f32_16x16x32_bf16 v[70:73], v[178:181], v[2:5], 0
	v_mfma_f32_16x16x32_bf16 v[62:65], v[186:189], v[2:5], 0
	v_mfma_f32_16x16x32_bf16 v[248:251], v[194:197], v[2:5], 0
	v_mfma_f32_16x16x32_bf16 v[78:81], v[174:177], v[6:9], v[78:81]
	v_mfma_f32_16x16x32_bf16 v[74:77], v[170:173], v[10:13], 0
	v_mfma_f32_16x16x32_bf16 v[70:73], v[182:185], v[6:9], v[70:73]
	v_mfma_f32_16x16x32_bf16 v[66:69], v[178:181], v[10:13], 0
	v_mfma_f32_16x16x32_bf16 v[62:65], v[190:193], v[6:9], v[62:65]
	v_mfma_f32_16x16x32_bf16 v[58:61], v[186:189], v[10:13], 0
	v_mfma_f32_16x16x32_bf16 v[248:251], v[204:207], v[6:9], v[248:251]
	v_mfma_f32_16x16x32_bf16 v[252:255], v[194:197], v[10:13], 0
	v_mfma_f32_16x16x32_bf16 v[74:77], v[174:177], v[14:17], v[74:77]
	v_mfma_f32_16x16x32_bf16 v[66:69], v[182:185], v[14:17], v[66:69]
	v_mfma_f32_16x16x32_bf16 v[58:61], v[190:193], v[14:17], v[58:61]
	v_mfma_f32_16x16x32_bf16 v[252:255], v[204:207], v[14:17], v[252:255]
	v_mfma_f32_16x16x32_bf16 v[46:49], v[170:173], v[208:211], 0
	v_mfma_f32_16x16x32_bf16 v[42:45], v[170:173], v[216:219], 0
	v_mfma_f32_16x16x32_bf16 v[38:41], v[178:181], v[208:211], 0
	v_mfma_f32_16x16x32_bf16 v[34:37], v[178:181], v[216:219], 0
	v_mfma_f32_16x16x32_bf16 v[30:33], v[186:189], v[208:211], 0
	v_mfma_f32_16x16x32_bf16 v[26:29], v[186:189], v[216:219], 0
	v_mfma_f32_16x16x32_bf16 v[22:25], v[194:197], v[208:211], 0
	v_mfma_f32_16x16x32_bf16 v[18:21], v[194:197], v[216:219], 0
	v_mfma_f32_16x16x32_bf16 v[46:49], v[174:177], v[212:215], v[46:49]
	v_mfma_f32_16x16x32_bf16 v[42:45], v[174:177], v[220:223], v[42:45]
	v_mfma_f32_16x16x32_bf16 v[38:41], v[182:185], v[212:215], v[38:41]
	v_mfma_f32_16x16x32_bf16 v[34:37], v[182:185], v[220:223], v[34:37]
	v_mfma_f32_16x16x32_bf16 v[30:33], v[190:193], v[212:215], v[30:33]
	v_mfma_f32_16x16x32_bf16 v[26:29], v[190:193], v[220:223], v[26:29]
	v_mfma_f32_16x16x32_bf16 v[22:25], v[204:207], v[212:215], v[22:25]
	v_mfma_f32_16x16x32_bf16 v[18:21], v[204:207], v[220:223], v[18:21]
	s_barrier
	s_setprio 0
	s_addk_i32 s38, 0x100
	s_mov_b32 m0, s57
	ds_read_b128 v[54:57], v163 offset:32768
	ds_read_b128 v[170:173], v163 offset:33792
	ds_read_b128 v[174:177], v164 offset:32768
	ds_read_b128 v[178:181], v164 offset:33792
	ds_read_b128 v[182:185], v165 offset:32768
	ds_read_b128 v[186:189], v165 offset:33792
	ds_read_b128 v[190:193], v166 offset:32768
	ds_read_b128 v[194:197], v166 offset:33792
	buffer_load_dwordx4 v148, s[8:11], s38 offen lds
	s_mov_b32 m0, s56
	s_nop 0
	buffer_load_dwordx4 v149, s[8:11], s38 offen lds
	s_addk_i32 s58, 0x180
	s_mov_b32 m0, s75
	ds_read_b128 v[204:207], v169
	ds_read_b128 v[208:211], v169 offset:1024
	ds_read_b128 v[212:215], v169 offset:2048
	ds_read_b128 v[216:219], v169 offset:3072
	buffer_load_dwordx4 v148, s[4:7], s58 offen lds
	s_mov_b32 m0, s74
	s_nop 0
	buffer_load_dwordx4 v149, s[4:7], s58 offen lds
	s_waitcnt vmcnt(8) lgkmcnt(0)
	s_setprio 1
	s_barrier
	v_mfma_f32_16x16x32_bf16 v[138:141], v[54:57], v[232:235], v[138:141]
	v_mfma_f32_16x16x32_bf16 v[142:145], v[54:57], v[240:243], v[142:145]
	v_mfma_f32_16x16x32_bf16 v[134:137], v[174:177], v[232:235], v[134:137]
	v_mfma_f32_16x16x32_bf16 v[130:133], v[174:177], v[240:243], v[130:133]
	v_mfma_f32_16x16x32_bf16 v[126:129], v[182:185], v[232:235], v[126:129]
	v_mfma_f32_16x16x32_bf16 v[122:125], v[182:185], v[240:243], v[122:125]
	v_mfma_f32_16x16x32_bf16 v[118:121], v[190:193], v[232:235], v[118:121]
	v_mfma_f32_16x16x32_bf16 v[114:117], v[190:193], v[240:243], v[114:117]
	v_mfma_f32_16x16x32_bf16 v[138:141], v[170:173], v[236:239], v[138:141]
	v_mfma_f32_16x16x32_bf16 v[142:145], v[170:173], v[244:247], v[142:145]
	v_mfma_f32_16x16x32_bf16 v[134:137], v[178:181], v[236:239], v[134:137]
	v_mfma_f32_16x16x32_bf16 v[130:133], v[178:181], v[244:247], v[130:133]
	v_mfma_f32_16x16x32_bf16 v[126:129], v[186:189], v[236:239], v[126:129]
	v_mfma_f32_16x16x32_bf16 v[122:125], v[186:189], v[244:247], v[122:125]
	v_mfma_f32_16x16x32_bf16 v[118:121], v[194:197], v[236:239], v[118:121]
	v_mfma_f32_16x16x32_bf16 v[114:117], v[194:197], v[244:247], v[114:117]
	v_mfma_f32_16x16x32_bf16 v[110:113], v[54:57], v[204:207], v[110:113]
	v_mfma_f32_16x16x32_bf16 v[54:57], v[54:57], v[212:215], v[106:109]
	v_mfma_f32_16x16x32_bf16 v[106:109], v[170:173], v[216:219], v[54:57]
	v_mfma_f32_16x16x32_bf16 v[54:57], v[174:177], v[204:207], v[102:105]
	v_mfma_f32_16x16x32_bf16 v[102:105], v[178:181], v[208:211], v[54:57]
	v_mfma_f32_16x16x32_bf16 v[54:57], v[174:177], v[212:215], v[98:101]
	v_mfma_f32_16x16x32_bf16 v[98:101], v[178:181], v[216:219], v[54:57]
	v_mfma_f32_16x16x32_bf16 v[54:57], v[182:185], v[204:207], v[94:97]
	v_mfma_f32_16x16x32_bf16 v[94:97], v[186:189], v[208:211], v[54:57]
	v_mfma_f32_16x16x32_bf16 v[54:57], v[182:185], v[212:215], v[90:93]
	v_mfma_f32_16x16x32_bf16 v[90:93], v[186:189], v[216:219], v[54:57]
	v_mfma_f32_16x16x32_bf16 v[54:57], v[190:193], v[204:207], v[86:89]
	v_mfma_f32_16x16x32_bf16 v[86:89], v[194:197], v[208:211], v[54:57]
	v_mfma_f32_16x16x32_bf16 v[54:57], v[190:193], v[212:215], v[82:85]
	v_mfma_f32_16x16x32_bf16 v[110:113], v[170:173], v[208:211], v[110:113]
	v_mfma_f32_16x16x32_bf16 v[82:85], v[194:197], v[216:219], v[54:57]
	s_barrier
; #define STAGE(PP, RSRC, br, kt) do { const int _so = ((br) * K + (kt) * BK) * 2; \
;       __builtin_amdgcn_raw_ptr_buffer_load_lds(RSRC, LDSP((char*)(PP) + ldsoff), 16, voff0, _so, 0, 0); \
;       __builtin_amdgcn_raw_ptr_buffer_load_lds(RSRC, LDSP((char*)(PP) + ldsoff + 8192), 16, voff1, _so, 0, 0); \
;     } while (0)
; #define LDA(dst, b, h) for (int m = 0; m < 4; ++m) for (int k = 0; k < 2; ++k) \
;     dst[m][k] = *reinterpret_cast<const bf16x8*>((char*)SA(b, h) + lds_byte(wr * 64 + m * 16 + fr, k * 32 + fq * 8))
; #define LDB(dst, b, h) for (int n = 0; n < 2; ++n) for (int k = 0; k < 2; ++k) \
;     dst[n][k] = *reinterpret_cast<const bf16x8*>((char*)SB(b, h) + lds_byte(wc * 32 + n * 16 + fr, k * 32 + fq * 8))
; #define MMA(ai, bj, At_, Bt_) do { __builtin_amdgcn_s_setprio(1); \
;     for (int m = 0; m < 4; ++m) for (int n = 0; n < 2; ++n) for (int k = 0; k < 2; ++k) \
;       acc[ai][bj][m][n] = __builtin_amdgcn_mfma_f32_16x16x32_bf16(At_[m][k], Bt_[n][k], acc[ai][bj][m][n], 0, 0, 0); \
;     __builtin_amdgcn_s_setprio(0); } while (0)
; #define WAIT_V(n) asm volatile("s_waitcnt vmcnt(" #n ")" ::: "memory")
; #define WAIT_L(n) asm volatile("s_waitcnt lgkmcnt(" #n ")" ::: "memory")
; #define BAR __builtin_amdgcn_s_barrier()
; #define SCHED __builtin_amdgcn_sched_barrier(0)
; __device__ __forceinline__ void gemm_tile(const Params& P, const GArgs& ga, const TileDesc& td, int wid_s) {
;     ...
;   for (int t = 0; t < nt - 2; t += 2) {
;     LDA(At, 0, 0); STAGE(SA(1, 1), A, brow + HALF, t + 1);
;     WAIT_L(8); BAR; WAIT_L(0); MMA(0, 0, At, B0); BAR; SCHED;
;     LDB(B1, 0, 1); STAGE(SB(0, 0), Bt, bcol, t + 2);
;     BAR; WAIT_L(0); MMA(0, 1, At, B1); BAR;
;     ...
;     LDB(B1, 1, 1); STAGE(SB(1, 0), Bt, bcol, t + 3);
;     BAR; WAIT_L(0); MMA(0, 1, At, B1); BAR;
;     LDA(At, 1, 1); STAGE(SA(1, 0), A, brow, t + 3);
;     WAIT_V(4); BAR; WAIT_L(0); MMA(1, 0, At, B0); BAR; SCHED;
;     LDB(B0, 0, 0); STAGE(SB(1, 1), Bt, bcol + HALF, t + 3);
;     BAR; MMA(1, 1, At, B1); BAR;
;   }
	s_setprio 0
	s_addk_i32 s40, 0x180
	s_mov_b32 m0, s83
	ds_read_b128 v[170:173], v163 offset:49152
	ds_read_b128 v[174:177], v163 offset:50176
	ds_read_b128 v[178:181], v164 offset:49152
	ds_read_b128 v[182:185], v164 offset:50176
	ds_read_b128 v[186:189], v165 offset:49152
	ds_read_b128 v[190:193], v165 offset:50176
	ds_read_b128 v[194:197], v166 offset:49152
	ds_read_b128 v[220:223], v166 offset:50176
	buffer_load_dwordx4 v148, s[8:11], s40 offen lds
	s_mov_b32 m0, s82
	s_nop 0
	buffer_load_dwordx4 v149, s[8:11], s40 offen lds
	s_mov_b32 m0, s69
	s_addk_i32 s33, 0x180
	buffer_load_dwordx4 v148, s[4:7], s33 offen lds
	s_mov_b32 m0, s68
	s_nop 0
	buffer_load_dwordx4 v149, s[4:7], s33 offen lds
	ds_read_b128 v[2:5], v162
	ds_read_b128 v[6:9], v162 offset:1024
	ds_read_b128 v[10:13], v162 offset:2048
	ds_read_b128 v[14:17], v162 offset:3072
	s_addk_i32 s99, 0x100
	s_cmp_lt_i32 vcc_lo, s0
	s_waitcnt vmcnt(8) lgkmcnt(0)
	s_setprio 1
	s_barrier
	v_mfma_f32_16x16x32_bf16 v[54:57], v[170:173], v[232:235], v[78:81]
	v_mfma_f32_16x16x32_bf16 v[78:81], v[174:177], v[236:239], v[54:57]
	v_mfma_f32_16x16x32_bf16 v[54:57], v[170:173], v[240:243], v[74:77]
	v_mfma_f32_16x16x32_bf16 v[74:77], v[174:177], v[244:247], v[54:57]
	v_mfma_f32_16x16x32_bf16 v[54:57], v[178:181], v[232:235], v[70:73]
	v_mfma_f32_16x16x32_bf16 v[70:73], v[182:185], v[236:239], v[54:57]
	v_mfma_f32_16x16x32_bf16 v[54:57], v[178:181], v[240:243], v[66:69]
	v_mfma_f32_16x16x32_bf16 v[66:69], v[182:185], v[244:247], v[54:57]
	v_mfma_f32_16x16x32_bf16 v[54:57], v[186:189], v[232:235], v[62:65]
	v_mfma_f32_16x16x32_bf16 v[62:65], v[190:193], v[236:239], v[54:57]
	v_mfma_f32_16x16x32_bf16 v[54:57], v[186:189], v[240:243], v[58:61]
	v_mfma_f32_16x16x32_bf16 v[248:251], v[194:197], v[232:235], v[248:251]
	v_mfma_f32_16x16x32_bf16 v[58:61], v[190:193], v[244:247], v[54:57]
	v_mfma_f32_16x16x32_bf16 v[54:57], v[220:223], v[236:239], v[248:251]
	v_mfma_f32_16x16x32_bf16 v[248:251], v[194:197], v[240:243], v[252:255]
	v_mfma_f32_16x16x32_bf16 v[50:53], v[220:223], v[244:247], v[248:251]
	v_mfma_f32_16x16x32_bf16 v[46:49], v[170:173], v[204:207], v[46:49]
	v_mfma_f32_16x16x32_bf16 v[42:45], v[170:173], v[212:215], v[42:45]
	v_mfma_f32_16x16x32_bf16 v[38:41], v[178:181], v[204:207], v[38:41]
	v_mfma_f32_16x16x32_bf16 v[34:37], v[178:181], v[212:215], v[34:37]
	v_mfma_f32_16x16x32_bf16 v[30:33], v[186:189], v[204:207], v[30:33]
	v_mfma_f32_16x16x32_bf16 v[26:29], v[186:189], v[212:215], v[26:29]
	v_mfma_f32_16x16x32_bf16 v[22:25], v[194:197], v[204:207], v[22:25]
	v_mfma_f32_16x16x32_bf16 v[18:21], v[194:197], v[212:215], v[18:21]
	v_mfma_f32_16x16x32_bf16 v[46:49], v[174:177], v[208:211], v[46:49]
	v_mfma_f32_16x16x32_bf16 v[42:45], v[174:177], v[216:219], v[42:45]
	v_mfma_f32_16x16x32_bf16 v[38:41], v[182:185], v[208:211], v[38:41]
	v_mfma_f32_16x16x32_bf16 v[34:37], v[182:185], v[216:219], v[34:37]
	v_mfma_f32_16x16x32_bf16 v[30:33], v[190:193], v[208:211], v[30:33]
	v_mfma_f32_16x16x32_bf16 v[26:29], v[190:193], v[216:219], v[26:29]
	v_mfma_f32_16x16x32_bf16 v[22:25], v[220:223], v[208:211], v[22:25]
	v_mfma_f32_16x16x32_bf16 v[18:21], v[220:223], v[216:219], v[18:21]
	s_barrier
	s_setprio 0
	s_cbranch_scc0 .Lml_exit
.LBB0_308:
	s_add_i32 s38, s1, s99
	s_add_i32 s6, s38, 0x80
	s_mov_b32 m0, s23
	ds_read_b128 v[170:173], v163
	ds_read_b128 v[174:177], v163 offset:1024
	ds_read_b128 v[178:181], v164
	ds_read_b128 v[182:185], v164 offset:1024
	ds_read_b128 v[186:189], v165
	ds_read_b128 v[190:193], v165 offset:1024
	ds_read_b128 v[194:197], v166
	ds_read_b128 v[204:207], v166 offset:1024
	buffer_load_dwordx4 v148, s[8:11], s6 offen lds
	s_mov_b32 m0, s22
	s_nop 0
	buffer_load_dwordx4 v149, s[8:11], s6 offen lds
	s_mul_i32 s6, s49, s15
	s_add_i32 s58, s6, s99
	s_mov_b32 m0, s88
	s_add_i32 vcc_hi, s58, 0x100
	s_mov_b32 s6, s10
	s_mov_b32 s7, s11
	ds_read_b128 v[208:211], v167
	ds_read_b128 v[212:215], v167 offset:1024
	ds_read_b128 v[216:219], v167 offset:2048
	ds_read_b128 v[220:223], v167 offset:3072
	buffer_load_dwordx4 v148, s[4:7], vcc_hi offen lds
	s_mov_b32 m0, s89
	s_add_i32 vcc_lo, vcc_lo, 2
	buffer_load_dwordx4 v149, s[4:7], vcc_hi offen lds
	s_waitcnt vmcnt(8) lgkmcnt(0)
	s_setprio 1
	s_barrier
	v_mfma_f32_16x16x32_bf16 v[138:141], v[170:173], v[2:5], v[138:141]
	v_mfma_f32_16x16x32_bf16 v[142:145], v[170:173], v[10:13], v[142:145]
	v_mfma_f32_16x16x32_bf16 v[134:137], v[178:181], v[2:5], v[134:137]
	v_mfma_f32_16x16x32_bf16 v[130:133], v[178:181], v[10:13], v[130:133]
	v_mfma_f32_16x16x32_bf16 v[126:129], v[186:189], v[2:5], v[126:129]
	v_mfma_f32_16x16x32_bf16 v[122:125], v[186:189], v[10:13], v[122:125]
	v_mfma_f32_16x16x32_bf16 v[118:121], v[194:197], v[2:5], v[118:121]
	v_mfma_f32_16x16x32_bf16 v[114:117], v[194:197], v[10:13], v[114:117]
	v_mfma_f32_16x16x32_bf16 v[138:141], v[174:177], v[6:9], v[138:141]
	v_mfma_f32_16x16x32_bf16 v[142:145], v[174:177], v[14:17], v[142:145]
	v_mfma_f32_16x16x32_bf16 v[134:137], v[182:185], v[6:9], v[134:137]
	v_mfma_f32_16x16x32_bf16 v[130:133], v[182:185], v[14:17], v[130:133]
	v_mfma_f32_16x16x32_bf16 v[126:129], v[190:193], v[6:9], v[126:129]
	v_mfma_f32_16x16x32_bf16 v[122:125], v[190:193], v[14:17], v[122:125]
	v_mfma_f32_16x16x32_bf16 v[118:121], v[204:207], v[6:9], v[118:121]
	v_mfma_f32_16x16x32_bf16 v[114:117], v[204:207], v[14:17], v[114:117]
	v_mfma_f32_16x16x32_bf16 v[110:113], v[170:173], v[208:211], v[110:113]
	v_mfma_f32_16x16x32_bf16 v[106:109], v[170:173], v[216:219], v[106:109]
	v_mfma_f32_16x16x32_bf16 v[102:105], v[178:181], v[208:211], v[102:105]
	v_mfma_f32_16x16x32_bf16 v[98:101], v[178:181], v[216:219], v[98:101]
	v_mfma_f32_16x16x32_bf16 v[94:97], v[186:189], v[208:211], v[94:97]
	v_mfma_f32_16x16x32_bf16 v[90:93], v[186:189], v[216:219], v[90:93]
	v_mfma_f32_16x16x32_bf16 v[86:89], v[194:197], v[208:211], v[86:89]
	v_mfma_f32_16x16x32_bf16 v[82:85], v[194:197], v[216:219], v[82:85]
	v_mfma_f32_16x16x32_bf16 v[110:113], v[174:177], v[212:215], v[110:113]
	v_mfma_f32_16x16x32_bf16 v[106:109], v[174:177], v[220:223], v[106:109]
	v_mfma_f32_16x16x32_bf16 v[102:105], v[182:185], v[212:215], v[102:105]
	v_mfma_f32_16x16x32_bf16 v[98:101], v[182:185], v[220:223], v[98:101]
	v_mfma_f32_16x16x32_bf16 v[94:97], v[190:193], v[212:215], v[94:97]
	v_mfma_f32_16x16x32_bf16 v[90:93], v[190:193], v[220:223], v[90:93]
	v_mfma_f32_16x16x32_bf16 v[86:89], v[204:207], v[212:215], v[86:89]
	v_mfma_f32_16x16x32_bf16 v[82:85], v[204:207], v[220:223], v[82:85]
	s_barrier
; #define STAGE(PP, RSRC, br, kt) do { const int _so = ((br) * K + (kt) * BK) * 2; \
;       __builtin_amdgcn_raw_ptr_buffer_load_lds(RSRC, LDSP((char*)(PP) + ldsoff), 16, voff0, _so, 0, 0); \
;       __builtin_amdgcn_raw_ptr_buffer_load_lds(RSRC, LDSP((char*)(PP) + ldsoff + 8192), 16, voff1, _so, 0, 0); \
;     } while (0)
; #define LDA(dst, b, h) for (int m = 0; m < 4; ++m) for (int k = 0; k < 2; ++k) \
;     dst[m][k] = *reinterpret_cast<const bf16x8*>((char*)SA(b, h) + lds_byte(wr * 64 + m * 16 + fr, k * 32 + fq * 8))
; #define LDB(dst, b, h) for (int n = 0; n < 2; ++n) for (int k = 0; k < 2; ++k) \
;     dst[n][k] = *reinterpret_cast<const bf16x8*>((char*)SB(b, h) + lds_byte(wc * 32 + n * 16 + fr, k * 32 + fq * 8))
; #define MMA(ai, bj, At_, Bt_) do { __builtin_amdgcn_s_setprio(1); \
;     for (int m = 0; m < 4; ++m) for (int n = 0; n < 2; ++n) for (int k = 0; k < 2; ++k) \
;       acc[ai][bj][m][n] = __builtin_amdgcn_mfma_f32_16x16x32_bf16(At_[m][k], Bt_[n][k], acc[ai][bj][m][n], 0, 0, 0); \
;     __builtin_amdgcn_s_setprio(0); } while (0)
; #define WAIT_V(n) asm volatile("s_waitcnt vmcnt(" #n ")" ::: "memory")
; #define WAIT_L(n) asm volatile("s_waitcnt lgkmcnt(" #n ")" ::: "memory")
; #define BAR __builtin_amdgcn_s_barrier()
; #define SCHED __builtin_amdgcn_sched_barrier(0)
; __device__ __forceinline__ void gemm_tile(const Params& P, const GArgs& ga, const TileDesc& td, int wid_s) {
;     ...
;   for (int t = 0; t < nt - 2; t += 2) {
;     LDA(At, 0, 0); STAGE(SA(1, 1), A, brow + HALF, t + 1);
;     WAIT_L(8); BAR; WAIT_L(0); MMA(0, 0, At, B0); BAR; SCHED;
;     LDB(B1, 0, 1); STAGE(SB(0, 0), Bt, bcol, t + 2);
;     BAR; WAIT_L(0); MMA(0, 1, At, B1); BAR;
;     LDA(At, 0, 1); STAGE(SA(0, 0), A, brow, t + 2);
;     WAIT_V(4); BAR; WAIT_L(0); MMA(1, 0, At, B0); BAR; SCHED;
;     LDB(B0, 1, 0); STAGE(SB(0, 1), Bt, bcol + HALF, t + 2);
;     BAR; MMA(1, 1, At, B1); BAR;
;     LDA(At, 1, 0); STAGE(SA(0, 1), A, brow + HALF, t + 2);
;     WAIT_L(8); BAR; WAIT_L(0); MMA(0, 0, At, B0); BAR; SCHED;
;     LDB(B1, 1, 1); STAGE(SB(1, 0), Bt, bcol, t + 3);
;     BAR; WAIT_L(0); MMA(0, 1, At, B1); BAR;
;     LDA(At, 1, 1); STAGE(SA(1, 0), A, brow, t + 3);
;     WAIT_V(4); BAR; WAIT_L(0); MMA(1, 0, At, B0); BAR; SCHED;
;     LDB(B0, 0, 0); STAGE(SB(1, 1), Bt, bcol + HALF, t + 3);
;     BAR; MMA(1, 1, At, B1); BAR;
;   }
	s_setprio 0
	s_mul_i32 vcc_hi, s49, s86
	s_add_i32 s40, vcc_hi, s99
	s_add_i32 vcc_hi, s40, 0x100
	s_mov_b32 m0, s52
	ds_read_b128 v[170:173], v163 offset:16384
	ds_read_b128 v[174:177], v163 offset:17408
	ds_read_b128 v[178:181], v164 offset:16384
	ds_read_b128 v[182:185], v164 offset:17408
	ds_read_b128 v[186:189], v165 offset:16384
	ds_read_b128 v[190:193], v165 offset:17408
	ds_read_b128 v[194:197], v166 offset:16384
	ds_read_b128 v[204:207], v166 offset:17408
	buffer_load_dwordx4 v148, s[8:11], vcc_hi offen lds
	s_mov_b32 m0, s94
	s_nop 0
	buffer_load_dwordx4 v149, s[8:11], vcc_hi offen lds
	s_add_i32 s33, s98, s99
	s_add_i32 vcc_hi, s33, 0x100
	s_mov_b32 m0, s95
	ds_read_b128 v[232:235], v168
	ds_read_b128 v[236:239], v168 offset:1024
	ds_read_b128 v[240:243], v168 offset:2048
	ds_read_b128 v[244:247], v168 offset:3072
	buffer_load_dwordx4 v148, s[4:7], vcc_hi offen lds
	s_mov_b32 m0, s3
	s_nop 0
	buffer_load_dwordx4 v149, s[4:7], vcc_hi offen lds
	s_waitcnt vmcnt(8) lgkmcnt(0)
	s_setprio 1
	s_barrier
	v_mfma_f32_16x16x32_bf16 v[78:81], v[170:173], v[2:5], v[78:81]
	v_mfma_f32_16x16x32_bf16 v[70:73], v[178:181], v[2:5], v[70:73]
	v_mfma_f32_16x16x32_bf16 v[62:65], v[186:189], v[2:5], v[62:65]
	v_mfma_f32_16x16x32_bf16 v[248:251], v[194:197], v[2:5], v[54:57]
	v_mfma_f32_16x16x32_bf16 v[78:81], v[174:177], v[6:9], v[78:81]
	v_mfma_f32_16x16x32_bf16 v[74:77], v[170:173], v[10:13], v[74:77]
	v_mfma_f32_16x16x32_bf16 v[70:73], v[182:185], v[6:9], v[70:73]
	v_mfma_f32_16x16x32_bf16 v[66:69], v[178:181], v[10:13], v[66:69]
	v_mfma_f32_16x16x32_bf16 v[62:65], v[190:193], v[6:9], v[62:65]
	v_mfma_f32_16x16x32_bf16 v[58:61], v[186:189], v[10:13], v[58:61]
	v_mfma_f32_16x16x32_bf16 v[248:251], v[204:207], v[6:9], v[248:251]
	v_mfma_f32_16x16x32_bf16 v[252:255], v[194:197], v[10:13], v[50:53]
	v_mfma_f32_16x16x32_bf16 v[74:77], v[174:177], v[14:17], v[74:77]
	v_mfma_f32_16x16x32_bf16 v[66:69], v[182:185], v[14:17], v[66:69]
	v_mfma_f32_16x16x32_bf16 v[58:61], v[190:193], v[14:17], v[58:61]
	v_mfma_f32_16x16x32_bf16 v[252:255], v[204:207], v[14:17], v[252:255]
	v_mfma_f32_16x16x32_bf16 v[46:49], v[170:173], v[208:211], v[46:49]
	v_mfma_f32_16x16x32_bf16 v[42:45], v[170:173], v[216:219], v[42:45]
	v_mfma_f32_16x16x32_bf16 v[38:41], v[178:181], v[208:211], v[38:41]
	v_mfma_f32_16x16x32_bf16 v[34:37], v[178:181], v[216:219], v[34:37]
	v_mfma_f32_16x16x32_bf16 v[30:33], v[186:189], v[208:211], v[30:33]
	v_mfma_f32_16x16x32_bf16 v[26:29], v[186:189], v[216:219], v[26:29]
	v_mfma_f32_16x16x32_bf16 v[22:25], v[194:197], v[208:211], v[22:25]
	v_mfma_f32_16x16x32_bf16 v[18:21], v[194:197], v[216:219], v[18:21]
	v_mfma_f32_16x16x32_bf16 v[46:49], v[174:177], v[212:215], v[46:49]
	v_mfma_f32_16x16x32_bf16 v[42:45], v[174:177], v[220:223], v[42:45]
	v_mfma_f32_16x16x32_bf16 v[38:41], v[182:185], v[212:215], v[38:41]
	v_mfma_f32_16x16x32_bf16 v[34:37], v[182:185], v[220:223], v[34:37]
	v_mfma_f32_16x16x32_bf16 v[30:33], v[190:193], v[212:215], v[30:33]
	v_mfma_f32_16x16x32_bf16 v[26:29], v[190:193], v[220:223], v[26:29]
	v_mfma_f32_16x16x32_bf16 v[22:25], v[204:207], v[212:215], v[22:25]
	v_mfma_f32_16x16x32_bf16 v[18:21], v[204:207], v[220:223], v[18:21]
	s_barrier
	s_setprio 0
	s_addk_i32 s38, 0x100
	s_mov_b32 m0, s57
	ds_read_b128 v[54:57], v163 offset:32768
	ds_read_b128 v[170:173], v163 offset:33792
	ds_read_b128 v[174:177], v164 offset:32768
	ds_read_b128 v[178:181], v164 offset:33792
	ds_read_b128 v[182:185], v165 offset:32768
	ds_read_b128 v[186:189], v165 offset:33792
	ds_read_b128 v[190:193], v166 offset:32768
	ds_read_b128 v[194:197], v166 offset:33792
	buffer_load_dwordx4 v148, s[8:11], s38 offen lds
	s_mov_b32 m0, s56
	s_nop 0
	buffer_load_dwordx4 v149, s[8:11], s38 offen lds
	s_addk_i32 s58, 0x180
	s_mov_b32 m0, s75
	ds_read_b128 v[204:207], v169
	ds_read_b128 v[208:211], v169 offset:1024
	ds_read_b128 v[212:215], v169 offset:2048
	ds_read_b128 v[216:219], v169 offset:3072
	buffer_load_dwordx4 v148, s[4:7], s58 offen lds
	s_mov_b32 m0, s74
	s_nop 0
	buffer_load_dwordx4 v149, s[4:7], s58 offen lds
	s_waitcnt vmcnt(8) lgkmcnt(0)
	s_setprio 1
	s_barrier
; #define STAGE(PP, RSRC, br, kt) do { const int _so = ((br) * K + (kt) * BK) * 2; \
;       __builtin_amdgcn_raw_ptr_buffer_load_lds(RSRC, LDSP((char*)(PP) + ldsoff), 16, voff0, _so, 0, 0); \
;       __builtin_amdgcn_raw_ptr_buffer_load_lds(RSRC, LDSP((char*)(PP) + ldsoff + 8192), 16, voff1, _so, 0, 0); \
;     } while (0)
; #define LDA(dst, b, h) for (int m = 0; m < 4; ++m) for (int k = 0; k < 2; ++k) \
;     dst[m][k] = *reinterpret_cast<const bf16x8*>((char*)SA(b, h) + lds_byte(wr * 64 + m * 16 + fr, k * 32 + fq * 8))
; #define LDB(dst, b, h) for (int n = 0; n < 2; ++n) for (int k = 0; k < 2; ++k) \
;     dst[n][k] = *reinterpret_cast<const bf16x8*>((char*)SB(b, h) + lds_byte(wc * 32 + n * 16 + fr, k * 32 + fq * 8))
; #define MMA(ai, bj, At_, Bt_) do { __builtin_amdgcn_s_setprio(1); \
;     for (int m = 0; m < 4; ++m) for (int n = 0; n < 2; ++n) for (int k = 0; k < 2; ++k) \
;       acc[ai][bj][m][n] = __builtin_amdgcn_mfma_f32_16x16x32_bf16(At_[m][k], Bt_[n][k], acc[ai][bj][m][n], 0, 0, 0); \
;     __builtin_amdgcn_s_setprio(0); } while (0)
; #define WAIT_V(n) asm volatile("s_waitcnt vmcnt(" #n ")" ::: "memory")
; #define WAIT_L(n) asm volatile("s_waitcnt lgkmcnt(" #n ")" ::: "memory")
; #define BAR __builtin_amdgcn_s_barrier()
; #define SCHED __builtin_amdgcn_sched_barrier(0)
; __device__ __forceinline__ void gemm_tile(const Params& P, const GArgs& ga, const TileDesc& td, int wid_s) {
;     ...
;   for (int t = 0; t < nt - 2; t += 2) {
;     LDA(At, 0, 0); STAGE(SA(1, 1), A, brow + HALF, t + 1);
;     WAIT_L(8); BAR; WAIT_L(0); MMA(0, 0, At, B0); BAR; SCHED;
;     LDB(B1, 0, 1); STAGE(SB(0, 0), Bt, bcol, t + 2);
;     BAR; WAIT_L(0); MMA(0, 1, At, B1); BAR;
;     LDA(At, 0, 1); STAGE(SA(0, 0), A, brow, t + 2);
;     WAIT_V(4); BAR; WAIT_L(0); MMA(1, 0, At, B0); BAR; SCHED;
;     LDB(B0, 1, 0); STAGE(SB(0, 1), Bt, bcol + HALF, t + 2);
;     BAR; MMA(1, 1, At, B1); BAR;
;     LDA(At, 1, 0); STAGE(SA(0, 1), A, brow + HALF, t + 2);
;     WAIT_L(8); BAR; WAIT_L(0); MMA(0, 0, At, B0); BAR; SCHED;
;     LDB(B1, 1, 1); STAGE(SB(1, 0), Bt, bcol, t + 3);
;     BAR; WAIT_L(0); MMA(0, 1, At, B1); BAR;
;     LDA(At, 1, 1); STAGE(SA(1, 0), A, brow, t + 3);
;     WAIT_V(4); BAR; WAIT_L(0); MMA(1, 0, At, B0); BAR; SCHED;
;     LDB(B0, 0, 0); STAGE(SB(1, 1), Bt, bcol + HALF, t + 3);
;     BAR; MMA(1, 1, At, B1); BAR;
;   }
	v_mfma_f32_16x16x32_bf16 v[138:141], v[54:57], v[232:235], v[138:141]
	v_mfma_f32_16x16x32_bf16 v[142:145], v[54:57], v[240:243], v[142:145]
	v_mfma_f32_16x16x32_bf16 v[134:137], v[174:177], v[232:235], v[134:137]
	v_mfma_f32_16x16x32_bf16 v[130:133], v[174:177], v[240:243], v[130:133]
	v_mfma_f32_16x16x32_bf16 v[126:129], v[182:185], v[232:235], v[126:129]
	v_mfma_f32_16x16x32_bf16 v[122:125], v[182:185], v[240:243], v[122:125]
	v_mfma_f32_16x16x32_bf16 v[118:121], v[190:193], v[232:235], v[118:121]
	v_mfma_f32_16x16x32_bf16 v[114:117], v[190:193], v[240:243], v[114:117]
	v_mfma_f32_16x16x32_bf16 v[138:141], v[170:173], v[236:239], v[138:141]
	v_mfma_f32_16x16x32_bf16 v[142:145], v[170:173], v[244:247], v[142:145]
	v_mfma_f32_16x16x32_bf16 v[134:137], v[178:181], v[236:239], v[134:137]
	v_mfma_f32_16x16x32_bf16 v[130:133], v[178:181], v[244:247], v[130:133]
	v_mfma_f32_16x16x32_bf16 v[126:129], v[186:189], v[236:239], v[126:129]
	v_mfma_f32_16x16x32_bf16 v[122:125], v[186:189], v[244:247], v[122:125]
	v_mfma_f32_16x16x32_bf16 v[118:121], v[194:197], v[236:239], v[118:121]
	v_mfma_f32_16x16x32_bf16 v[114:117], v[194:197], v[244:247], v[114:117]
	v_mfma_f32_16x16x32_bf16 v[110:113], v[54:57], v[204:207], v[110:113]
	v_mfma_f32_16x16x32_bf16 v[54:57], v[54:57], v[212:215], v[106:109]
	v_mfma_f32_16x16x32_bf16 v[106:109], v[170:173], v[216:219], v[54:57]
	v_mfma_f32_16x16x32_bf16 v[54:57], v[174:177], v[204:207], v[102:105]
	v_mfma_f32_16x16x32_bf16 v[102:105], v[178:181], v[208:211], v[54:57]
	v_mfma_f32_16x16x32_bf16 v[54:57], v[174:177], v[212:215], v[98:101]
	v_mfma_f32_16x16x32_bf16 v[98:101], v[178:181], v[216:219], v[54:57]
	v_mfma_f32_16x16x32_bf16 v[54:57], v[182:185], v[204:207], v[94:97]
	v_mfma_f32_16x16x32_bf16 v[94:97], v[186:189], v[208:211], v[54:57]
	v_mfma_f32_16x16x32_bf16 v[54:57], v[182:185], v[212:215], v[90:93]
	v_mfma_f32_16x16x32_bf16 v[90:93], v[186:189], v[216:219], v[54:57]
	v_mfma_f32_16x16x32_bf16 v[54:57], v[190:193], v[204:207], v[86:89]
	v_mfma_f32_16x16x32_bf16 v[86:89], v[194:197], v[208:211], v[54:57]
	v_mfma_f32_16x16x32_bf16 v[54:57], v[190:193], v[212:215], v[82:85]
	v_mfma_f32_16x16x32_bf16 v[110:113], v[170:173], v[208:211], v[110:113]
	v_mfma_f32_16x16x32_bf16 v[82:85], v[194:197], v[216:219], v[54:57]
	s_barrier
	s_setprio 0
	s_addk_i32 s40, 0x180
	s_mov_b32 m0, s83
	ds_read_b128 v[170:173], v163 offset:49152
	ds_read_b128 v[174:177], v163 offset:50176
	ds_read_b128 v[178:181], v164 offset:49152
	ds_read_b128 v[182:185], v164 offset:50176
	ds_read_b128 v[186:189], v165 offset:49152
	ds_read_b128 v[190:193], v165 offset:50176
	ds_read_b128 v[194:197], v166 offset:49152
	ds_read_b128 v[220:223], v166 offset:50176
	buffer_load_dwordx4 v148, s[8:11], s40 offen lds
	s_mov_b32 m0, s82
	s_nop 0
	buffer_load_dwordx4 v149, s[8:11], s40 offen lds
	s_mov_b32 m0, s69
	s_addk_i32 s33, 0x180
	buffer_load_dwordx4 v148, s[4:7], s33 offen lds
	s_mov_b32 m0, s68
	s_nop 0
	buffer_load_dwordx4 v149, s[4:7], s33 offen lds
	ds_read_b128 v[2:5], v162
	ds_read_b128 v[6:9], v162 offset:1024
	ds_read_b128 v[10:13], v162 offset:2048
	ds_read_b128 v[14:17], v162 offset:3072
	s_addk_i32 s99, 0x100
	s_cmp_lt_i32 vcc_lo, s0
	s_waitcnt vmcnt(8) lgkmcnt(0)
	s_setprio 1
	s_barrier
	v_mfma_f32_16x16x32_bf16 v[54:57], v[170:173], v[232:235], v[78:81]
	v_mfma_f32_16x16x32_bf16 v[78:81], v[174:177], v[236:239], v[54:57]
	v_mfma_f32_16x16x32_bf16 v[54:57], v[170:173], v[240:243], v[74:77]
	v_mfma_f32_16x16x32_bf16 v[74:77], v[174:177], v[244:247], v[54:57]
	v_mfma_f32_16x16x32_bf16 v[54:57], v[178:181], v[232:235], v[70:73]
	v_mfma_f32_16x16x32_bf16 v[70:73], v[182:185], v[236:239], v[54:57]
	v_mfma_f32_16x16x32_bf16 v[54:57], v[178:181], v[240:243], v[66:69]
	v_mfma_f32_16x16x32_bf16 v[66:69], v[182:185], v[244:247], v[54:57]
	v_mfma_f32_16x16x32_bf16 v[54:57], v[186:189], v[232:235], v[62:65]
	v_mfma_f32_16x16x32_bf16 v[62:65], v[190:193], v[236:239], v[54:57]
	v_mfma_f32_16x16x32_bf16 v[54:57], v[186:189], v[240:243], v[58:61]
	v_mfma_f32_16x16x32_bf16 v[248:251], v[194:197], v[232:235], v[248:251]
	v_mfma_f32_16x16x32_bf16 v[58:61], v[190:193], v[244:247], v[54:57]
	v_mfma_f32_16x16x32_bf16 v[54:57], v[220:223], v[236:239], v[248:251]
	v_mfma_f32_16x16x32_bf16 v[248:251], v[194:197], v[240:243], v[252:255]
	v_mfma_f32_16x16x32_bf16 v[50:53], v[220:223], v[244:247], v[248:251]
	v_mfma_f32_16x16x32_bf16 v[46:49], v[170:173], v[204:207], v[46:49]
	v_mfma_f32_16x16x32_bf16 v[42:45], v[170:173], v[212:215], v[42:45]
	v_mfma_f32_16x16x32_bf16 v[38:41], v[178:181], v[204:207], v[38:41]
	v_mfma_f32_16x16x32_bf16 v[34:37], v[178:181], v[212:215], v[34:37]
	v_mfma_f32_16x16x32_bf16 v[30:33], v[186:189], v[204:207], v[30:33]
	v_mfma_f32_16x16x32_bf16 v[26:29], v[186:189], v[212:215], v[26:29]
	v_mfma_f32_16x16x32_bf16 v[22:25], v[194:197], v[204:207], v[22:25]
	v_mfma_f32_16x16x32_bf16 v[18:21], v[194:197], v[212:215], v[18:21]
	v_mfma_f32_16x16x32_bf16 v[46:49], v[174:177], v[208:211], v[46:49]
	v_mfma_f32_16x16x32_bf16 v[42:45], v[174:177], v[216:219], v[42:45]
	v_mfma_f32_16x16x32_bf16 v[38:41], v[182:185], v[208:211], v[38:41]
	v_mfma_f32_16x16x32_bf16 v[34:37], v[182:185], v[216:219], v[34:37]
	v_mfma_f32_16x16x32_bf16 v[30:33], v[190:193], v[208:211], v[30:33]
	v_mfma_f32_16x16x32_bf16 v[26:29], v[190:193], v[216:219], v[26:29]
	v_mfma_f32_16x16x32_bf16 v[22:25], v[220:223], v[208:211], v[22:25]
	v_mfma_f32_16x16x32_bf16 v[18:21], v[220:223], v[216:219], v[18:21]
	s_barrier
	s_setprio 0
	s_cbranch_scc1 .LBB0_308
